# adds: S5 carry-in state loads batched per unrolled step; swa_prompt K/V staging with full-line loads
# speedup vs baseline: 1.0186x; 1.0093x over previous
; template <int MODE>
; __device__ __forceinline__ void ssm_unit(const Ctx& P, int li, int g, int cidx, LAS unsigned char* hs, const bf16_t* H, bf16_t* Z, float* E, int lane) {
;     ...
;         for (int s = 0; s < 2; ++s) { float pr = lre[s], pi = lim[s];
; #pragma unroll
;             for (int q = 0; q < 7; ++q) { const float t = pr * pr - pi * pi; pi = 2.0f * pr * pi; pr = t; }
;             const int p = c + 32 * s;
; #pragma unroll 8
;             for (int j = 0; j < cidx; ++j) { const float* ep = E + (((size_t)(half * 32 + j) * 128 + g) * 64 + p) * 2; const float er = ep[0], ei = ep[1];
;                 const float t = hr[s] * pr - hi[s] * pi + er; hi[s] = hr[s] * pi + hi[s] * pr + ei; hr[s] = t; } }
.LBB0_69:
	v_add_co_u32_e32 v228, vcc, 0xfff90000, v2
	s_nop 1
	v_addc_co_u32_e32 v229, vcc, -1, v3, vcc
	global_load_dwordx2 v[212:213], v[228:229], off offset:-4
	v_add_co_u32_e32 v228, vcc, s63, v2
	s_nop 1
	v_addc_co_u32_e32 v229, vcc, -1, v3, vcc
	global_load_dwordx2 v[214:215], v[228:229], off offset:-4
	v_add_co_u32_e32 v228, vcc, s31, v2
	s_nop 1
	v_addc_co_u32_e32 v229, vcc, -1, v3, vcc
	global_load_dwordx2 v[216:217], v[228:229], off offset:-4
	v_add_co_u32_e32 v228, vcc, s46, v2
	s_nop 1
	v_addc_co_u32_e32 v229, vcc, -1, v3, vcc
	global_load_dwordx2 v[218:219], v[228:229], off offset:-4
	v_add_co_u32_e32 v228, vcc, s47, v2
	s_nop 1
	v_addc_co_u32_e32 v229, vcc, -1, v3, vcc
	global_load_dwordx2 v[220:221], v[228:229], off offset:-4
	v_add_co_u32_e32 v228, vcc, s48, v2
	s_nop 1
	v_addc_co_u32_e32 v229, vcc, -1, v3, vcc
	global_load_dwordx2 v[222:223], v[228:229], off offset:-4
	v_add_co_u32_e32 v228, vcc, s61, v2
	s_nop 1
	v_addc_co_u32_e32 v229, vcc, -1, v3, vcc
	global_load_dwordx2 v[224:225], v[228:229], off offset:-4
	global_load_dwordx2 v[226:227], v[2:3], off offset:-4
	s_waitcnt vmcnt(0)
	v_add_co_u32_e32 v8, vcc, 0xfff90000, v2
	v_mov_b32_e32 v12, v5
	s_nop 0
	v_addc_co_u32_e32 v9, vcc, -1, v3, vcc
	v_mov_b64_e32 v[8:9], v[212:213]
	v_mov_b32_e32 v13, v4
	v_pk_mul_f32 v[10:11], v[0:1], v[4:5]
	v_pk_mul_f32 v[4:5], v[0:1], v[12:13]
	v_sub_f32_e32 v7, v11, v10
	v_add_f32_e32 v4, v4, v5
	s_add_i32 s24, s24, 8
	s_waitcnt vmcnt(0)
	v_add_f32_e32 v10, v9, v4
	v_add_co_u32_e32 v4, vcc, s63, v2
	v_add_f32_e32 v11, v8, v7
	s_nop 0
	v_addc_co_u32_e32 v5, vcc, -1, v3, vcc
	v_mov_b64_e32 v[4:5], v[214:215]
	v_pk_mul_f32 v[8:9], v[0:1], v[10:11]
	v_mov_b32_e32 v12, v11
	v_mov_b32_e32 v13, v10
	v_sub_f32_e32 v7, v9, v8
	v_pk_mul_f32 v[10:11], v[0:1], v[12:13]
	s_waitcnt vmcnt(0)
	v_add_f32_e32 v9, v4, v7
	v_add_f32_e32 v4, v10, v11
	v_add_f32_e32 v8, v5, v4
	v_add_co_u32_e32 v4, vcc, s31, v2
	v_pk_mul_f32 v[10:11], v[0:1], v[8:9]
	s_nop 0
	v_addc_co_u32_e32 v5, vcc, -1, v3, vcc
	v_mov_b64_e32 v[4:5], v[216:217]
	v_mov_b32_e32 v12, v9
	v_mov_b32_e32 v13, v8
	v_sub_f32_e32 v7, v11, v10
	v_pk_mul_f32 v[8:9], v[0:1], v[12:13]
	s_waitcnt vmcnt(0)
	v_add_f32_e32 v11, v4, v7
	v_add_f32_e32 v4, v8, v9
	v_add_f32_e32 v10, v5, v4
	v_add_co_u32_e32 v4, vcc, s46, v2
	v_pk_mul_f32 v[8:9], v[0:1], v[10:11]
	s_nop 0
	v_addc_co_u32_e32 v5, vcc, -1, v3, vcc
	v_mov_b64_e32 v[4:5], v[218:219]
	v_mov_b32_e32 v12, v11
	v_mov_b32_e32 v13, v10
	v_sub_f32_e32 v7, v9, v8
	v_pk_mul_f32 v[10:11], v[0:1], v[12:13]
	s_waitcnt vmcnt(0)
	v_add_f32_e32 v9, v4, v7
	v_add_f32_e32 v4, v10, v11
	v_add_f32_e32 v8, v5, v4
	v_add_co_u32_e32 v4, vcc, s47, v2
	v_pk_mul_f32 v[10:11], v[0:1], v[8:9]
	s_nop 0
	v_addc_co_u32_e32 v5, vcc, -1, v3, vcc
	v_mov_b64_e32 v[4:5], v[220:221]
	v_mov_b32_e32 v12, v9
	v_mov_b32_e32 v13, v8
	v_sub_f32_e32 v7, v11, v10
	v_pk_mul_f32 v[8:9], v[0:1], v[12:13]
	s_waitcnt vmcnt(0)
	v_add_f32_e32 v11, v4, v7
	v_add_f32_e32 v4, v8, v9
	v_add_f32_e32 v10, v5, v4
	v_add_co_u32_e32 v4, vcc, s48, v2
	v_mov_b32_e32 v12, v11
	s_nop 0
	v_addc_co_u32_e32 v5, vcc, -1, v3, vcc
	v_mov_b64_e32 v[8:9], v[222:223]
	v_pk_mul_f32 v[4:5], v[0:1], v[10:11]
	v_mov_b32_e32 v13, v10
	v_sub_f32_e32 v4, v5, v4
	v_pk_mul_f32 v[10:11], v[0:1], v[12:13]
	s_waitcnt vmcnt(0)
	v_add_f32_e32 v5, v8, v4
	v_add_f32_e32 v4, v10, v11
	v_add_co_u32_e32 v8, vcc, s61, v2
	v_add_f32_e32 v4, v9, v4
	s_nop 0
	v_addc_co_u32_e32 v9, vcc, -1, v3, vcc
	v_mov_b64_e32 v[8:9], v[224:225]
	v_mov_b32_e32 v12, v5
	v_mov_b32_e32 v13, v4
	v_pk_mul_f32 v[10:11], v[0:1], v[4:5]
	v_pk_mul_f32 v[4:5], v[0:1], v[12:13]
	v_sub_f32_e32 v7, v11, v10
	v_add_f32_e32 v4, v4, v5
	v_cmp_eq_u32_e32 vcc, s24, v6
	s_or_b64 s[44:45], vcc, s[44:45]
	s_waitcnt vmcnt(0)
	v_add_f32_e32 v11, v8, v7
	v_add_f32_e32 v10, v9, v4
	v_mov_b64_e32 v[8:9], v[226:227]
	v_pk_mul_f32 v[4:5], v[0:1], v[10:11]
	v_mov_b32_e32 v12, v11
	v_mov_b32_e32 v13, v10
	v_sub_f32_e32 v4, v5, v4
	v_pk_mul_f32 v[10:11], v[0:1], v[12:13]
	v_lshl_add_u64 v[2:3], v[2:3], 0, s[50:51]
	s_waitcnt vmcnt(0)
	v_add_f32_e32 v5, v8, v4
	v_add_f32_e32 v4, v10, v11
	v_add_f32_e32 v4, v9, v4
	s_andn2_b64 exec, exec, s[44:45]
	s_cbranch_execnz .LBB0_69
	s_or_b64 exec, exec, s[44:45]
	v_mov_b32_e32 v2, v5
	v_mov_b32_e32 v3, v129
	v_mov_b32_e32 v136, v4
	v_mov_b32_e32 v137, v129
	v_mov_b64_e32 v[138:139], v[2:3]

; template <int MODE>
; __device__ __forceinline__ void ssm_unit(const Ctx& P, int li, int g, int cidx, LAS unsigned char* hs, const bf16_t* H, bf16_t* Z, float* E, int lane) {
;     ...
;         for (int s = 0; s < 2; ++s) { float pr = lre[s], pi = lim[s];
; #pragma unroll
;             for (int q = 0; q < 7; ++q) { const float t = pr * pr - pi * pi; pi = 2.0f * pr * pi; pr = t; }
;             const int p = c + 32 * s;
; #pragma unroll 8
;             for (int j = 0; j < cidx; ++j) { const float* ep = E + (((size_t)(half * 32 + j) * 128 + g) * 64 + p) * 2; const float er = ep[0], ei = ep[1];
;                 const float t = hr[s] * pr - hi[s] * pi + er; hi[s] = hr[s] * pi + hi[s] * pr + ei; hr[s] = t; } }
.LBB0_79:
	v_add_co_u32_e32 v228, vcc, 0xfff90000, v2
	s_nop 1
	v_addc_co_u32_e32 v229, vcc, -1, v3, vcc
	global_load_dwordx2 v[212:213], v[228:229], off offset:-4
	v_add_co_u32_e32 v228, vcc, s63, v2
	s_nop 1
	v_addc_co_u32_e32 v229, vcc, -1, v3, vcc
	global_load_dwordx2 v[214:215], v[228:229], off offset:-4
	v_add_co_u32_e32 v228, vcc, s31, v2
	s_nop 1
	v_addc_co_u32_e32 v229, vcc, -1, v3, vcc
	global_load_dwordx2 v[216:217], v[228:229], off offset:-4
	v_add_co_u32_e32 v228, vcc, s44, v2
	s_nop 1
	v_addc_co_u32_e32 v229, vcc, -1, v3, vcc
	global_load_dwordx2 v[218:219], v[228:229], off offset:-4
	v_add_co_u32_e32 v228, vcc, s45, v2
	s_nop 1
	v_addc_co_u32_e32 v229, vcc, -1, v3, vcc
	global_load_dwordx2 v[220:221], v[228:229], off offset:-4
	v_add_co_u32_e32 v228, vcc, s46, v2
	s_nop 1
	v_addc_co_u32_e32 v229, vcc, -1, v3, vcc
	global_load_dwordx2 v[222:223], v[228:229], off offset:-4
	v_add_co_u32_e32 v228, vcc, s61, v2
	s_nop 1
	v_addc_co_u32_e32 v229, vcc, -1, v3, vcc
	global_load_dwordx2 v[224:225], v[228:229], off offset:-4
	global_load_dwordx2 v[226:227], v[2:3], off offset:-4
	s_waitcnt vmcnt(0)
	v_add_co_u32_e32 v4, vcc, 0xfff90000, v2
	v_mov_b32_e32 v8, v137
	s_nop 0
	v_addc_co_u32_e32 v5, vcc, -1, v3, vcc
	v_mov_b64_e32 v[4:5], v[212:213]
	v_mov_b32_e32 v9, v139
	v_pk_mul_f32 v[8:9], v[0:1], v[8:9]
	v_mov_b32_e32 v10, v139
	v_mov_b32_e32 v11, v137
	v_sub_f32_e32 v7, v9, v8
	v_pk_mul_f32 v[10:11], v[0:1], v[10:11]
	s_add_i32 s24, s24, 8
	s_waitcnt vmcnt(0)
	v_add_f32_e32 v9, v4, v7
	v_add_f32_e32 v4, v10, v11
	v_add_f32_e32 v8, v5, v4
	v_add_co_u32_e32 v4, vcc, s63, v2
	v_pk_mul_f32 v[10:11], v[0:1], v[8:9]
	s_nop 0
	v_addc_co_u32_e32 v5, vcc, -1, v3, vcc
	v_mov_b64_e32 v[4:5], v[214:215]
	v_mov_b32_e32 v12, v9
	v_mov_b32_e32 v13, v8
	v_sub_f32_e32 v7, v11, v10
	v_pk_mul_f32 v[8:9], v[0:1], v[12:13]
	s_waitcnt vmcnt(0)
	v_add_f32_e32 v11, v4, v7
	v_add_f32_e32 v4, v8, v9
	v_add_f32_e32 v10, v5, v4
	v_add_co_u32_e32 v4, vcc, s31, v2
	v_pk_mul_f32 v[8:9], v[0:1], v[10:11]
	s_nop 0
	v_addc_co_u32_e32 v5, vcc, -1, v3, vcc
	v_mov_b64_e32 v[4:5], v[216:217]
	v_mov_b32_e32 v12, v11
	v_mov_b32_e32 v13, v10
	v_sub_f32_e32 v7, v9, v8
	v_pk_mul_f32 v[10:11], v[0:1], v[12:13]
	s_waitcnt vmcnt(0)
	v_add_f32_e32 v9, v4, v7
	v_add_f32_e32 v4, v10, v11
	v_add_f32_e32 v8, v5, v4
	v_add_co_u32_e32 v4, vcc, s44, v2
	v_pk_mul_f32 v[10:11], v[0:1], v[8:9]
	s_nop 0
	v_addc_co_u32_e32 v5, vcc, -1, v3, vcc
	v_mov_b64_e32 v[4:5], v[218:219]
	v_mov_b32_e32 v12, v9
	v_mov_b32_e32 v13, v8
	v_sub_f32_e32 v7, v11, v10
	v_pk_mul_f32 v[8:9], v[0:1], v[12:13]
	s_waitcnt vmcnt(0)
	v_add_f32_e32 v11, v4, v7
	v_add_f32_e32 v4, v8, v9
	v_add_f32_e32 v10, v5, v4
	v_add_co_u32_e32 v4, vcc, s45, v2
	v_pk_mul_f32 v[8:9], v[0:1], v[10:11]
	s_nop 0
	v_addc_co_u32_e32 v5, vcc, -1, v3, vcc
	v_mov_b64_e32 v[4:5], v[220:221]
	v_mov_b32_e32 v12, v11
	v_mov_b32_e32 v13, v10
	v_sub_f32_e32 v7, v9, v8
	v_pk_mul_f32 v[10:11], v[0:1], v[12:13]
	s_waitcnt vmcnt(0)
	v_add_f32_e32 v9, v4, v7
	v_add_f32_e32 v4, v10, v11
	v_add_f32_e32 v8, v5, v4
	v_add_co_u32_e32 v4, vcc, s46, v2
	v_mov_b32_e32 v12, v9
	s_nop 0
	v_addc_co_u32_e32 v5, vcc, -1, v3, vcc
	v_mov_b64_e32 v[10:11], v[222:223]
	v_pk_mul_f32 v[4:5], v[0:1], v[8:9]
	v_mov_b32_e32 v13, v8
	v_sub_f32_e32 v4, v5, v4
	v_pk_mul_f32 v[8:9], v[0:1], v[12:13]
	s_waitcnt vmcnt(0)
	v_add_f32_e32 v5, v10, v4
	v_add_f32_e32 v4, v8, v9
	v_add_co_u32_e32 v8, vcc, s61, v2
	v_add_f32_e32 v4, v11, v4
	s_nop 0
	v_addc_co_u32_e32 v9, vcc, -1, v3, vcc
	v_mov_b64_e32 v[8:9], v[224:225]
	v_mov_b32_e32 v12, v5
	v_mov_b32_e32 v13, v4
	v_pk_mul_f32 v[10:11], v[0:1], v[4:5]
	v_pk_mul_f32 v[4:5], v[0:1], v[12:13]
	v_sub_f32_e32 v7, v11, v10
	v_add_f32_e32 v4, v4, v5
	v_cmp_eq_u32_e32 vcc, s24, v6
	s_or_b64 s[42:43], vcc, s[42:43]
	s_waitcnt vmcnt(0)
	v_add_f32_e32 v10, v9, v4
	v_mov_b64_e32 v[4:5], v[226:227]
	v_add_f32_e32 v11, v8, v7
	v_pk_mul_f32 v[8:9], v[0:1], v[10:11]
	v_lshl_add_u64 v[2:3], v[2:3], 0, s[48:49]
	v_sub_f32_e32 v7, v9, v8
	v_mov_b32_e32 v8, v11
	v_mov_b32_e32 v9, v10
	v_pk_mul_f32 v[8:9], v[0:1], v[8:9]
	s_waitcnt vmcnt(0)
	v_add_f32_e32 v139, v4, v7
	v_add_f32_e32 v4, v8, v9
	v_add_f32_e32 v137, v5, v4
	s_andn2_b64 exec, exec, s[42:43]
	s_cbranch_execnz .LBB0_79
	s_or_b64 exec, exec, s[42:43]

; #define LAS __attribute__((address_space(3)))
; __device__ __forceinline__ void swa_prompt_unit(const Ctx& P, int li, int b, int qh, int n, LAS unsigned char* lds, const bf16_t* PROJ, bf16_t* H, int tid) {
;     ...
;     const long R0 = (long)b * SEQ + (long)n * 128;
; #pragma unroll
;     for (int r = 0; r < 4; ++r) { const int idx = tid + 512 * r, jj = idx & 255, seg = idx >> 8;
;         const bool valid = (n > 0) || (jj >= 128);
;         u32x4 kv = {0u, 0u, 0u, 0u}, vv = {0u, 0u, 0u, 0u};
;         if (valid) { const bf16_t* rp = PROJ + (size_t)(R0 - 128 + jj) * EIN + kvh * 64 + seg * 8; kv = *(const u32x4*)(rp + 5120); vv = *(const u32x4*)(rp + 5248); }
;         *(LAS u32x4*)(Ks + jj * 144 + seg * 16) = kv;
; #pragma unroll
;         for (int i = 0; i < 4; ++i) {
;             *(LAS bf16_t*)(VT + (seg * 8 + 2 * i) * 528 + jj * 2) = (bf16_t)(vv[i] & 0xffffu);
;             *(LAS bf16_t*)(VT + (seg * 8 + 2 * i + 1) * 528 + jj * 2) = (bf16_t)(vv[i] >> 16); } }
.Lmix_go:
	s_cmpk_gt_i32 s38, 0x3ff
	s_cbranch_scc1 .LBB0_469
	s_ashr_i32 s0, s38, 9
	s_and_b32 s4, s38, 31
	s_ashr_i32 s1, s0, 31
	s_lshl_b64 s[0:1], s[0:1], 12
	s_lshl_b32 s5, s4, 7
	s_or_b32 s0, s0, s5
	v_and_b32_e32 v128, 0xff, v47
	s_movk_i32 s20, 0xff80
	v_lshl_add_u64 v[0:1], v[128:129], 0, s[0:1]
	s_mov_b32 s21, -1
	v_lshl_add_u64 v[0:1], v[0:1], 0, s[20:21]
	v_mov_b64_e32 v[2:3], s[14:15]
	s_cmp_lg_u32 s4, 0
	v_mad_u64_u32 v[2:3], s[20:21], v0, s35, v[2:3]
	s_cselect_b64 s[4:5], -1, 0
	s_movk_i32 s18, 0x7f
	s_lshr_b32 s20, s38, 1
	v_cmp_lt_u32_e32 vcc, s18, v128
	v_mad_i32_i24 v3, v1, s35, v3
	s_and_b32 s24, s20, 0x80
	s_waitcnt vmcnt(10)
	v_mov_b32_e32 v6, 0
	s_or_b64 s[18:19], s[4:5], vcc
	s_waitcnt vmcnt(9)
	v_lshl_add_u64 v[10:11], v[2:3], 0, s[24:25]
	v_ashrrev_i32_e32 v1, 8, v47
	v_mov_b32_e32 v0, 0
	v_mov_b32_e32 v2, 0
	v_mov_b32_e32 v3, 0
	v_mov_b32_e32 v4, 0
	v_mov_b32_e32 v5, 0
	v_mov_b32_e32 v7, v6
	v_mov_b32_e32 v8, v6
	v_mov_b32_e32 v9, v6
	v_lshrrev_b32_e32 v200, 3, v47
	v_and_b32_e32 v201, 7, v47
	v_sub_u32_e32 v204, v200, v128
	v_mov_b32_e32 v205, 0
	v_mad_i64_i32 v[202:203], s[20:21], v204, s35, v[10:11]
	v_lshlrev_b32_e32 v204, 4, v201
	v_mul_u32_u24_e32 v244, 0x90, v200
	v_lshl_add_u64 v[202:203], v[202:203], 0, v[204:205]
	s_mov_b64 s[20:21], 0x2000
	v_mul_u32_u24_e32 v245, 0x1080, v201
	v_lshl_add_u64 v[202:203], v[202:203], 0, s[20:21]
	s_mov_b32 s20, 0xa8000
	s_mov_b32 s21, 0
	v_lshl_add_u32 v244, v201, 4, v244
	v_lshl_add_u32 v245, v200, 1, v245
	s_and_b64 vcc, exec, s[4:5]
	s_cbranch_vccz .Lswp_first_tile
	global_load_dwordx4 v[212:215], v[202:203], off offset:2048
	global_load_dwordx4 v[216:219], v[202:203], off offset:2304
	v_lshl_add_u64 v[202:203], v[202:203], 0, s[20:21]
	global_load_dwordx4 v[220:223], v[202:203], off offset:2048
	global_load_dwordx4 v[224:227], v[202:203], off offset:2304
	v_lshl_add_u64 v[202:203], v[202:203], 0, s[20:21]
	s_branch .Lswp_second_half
